# grid barrier: XCC leaders poll monotonic TOP counter (drop TOPGEN atomic hop); nloc/nx/xcc cached in SGPRs instead of 3 serialized flat LDS loads per barrier
# speedup vs baseline: 1.0604x; 1.0029x over previous
.LBB0_98:
	s_or_b64 exec, exec, s[40:41]
	v_readfirstlane_b32 s99, v2
	v_readfirstlane_b32 s100, v0
	v_readfirstlane_b32 s101, v1
	v_lshlrev_b32_e32 v1, 5, v1
	v_readlane_b32 s2, v254, 0
	v_add_u32_e32 v4, 0x140, v1
	v_mov_b32_e32 v5, 0
	v_readlane_b32 s3, v254, 1
	v_mov_b32_e32 v3, 1
	s_nop 0
	v_lshl_add_u64 v[6:7], v[4:5], 2, s[2:3]
	global_atomic_add v3, v[6:7], v3, off sc0
	v_cvt_f32_u32_e32 v4, v2
	v_sub_u32_e32 v6, 0, v2
	v_rcp_iflag_f32_e32 v4, v4
	s_nop 0
	v_mul_f32_e32 v4, 0x4f7ffffe, v4
	v_cvt_u32_f32_e32 v4, v4
	v_mul_lo_u32 v6, v6, v4
	v_mul_hi_u32 v6, v4, v6
	v_add_u32_e32 v4, v4, v6
	s_waitcnt vmcnt(0)
	v_mul_hi_u32 v4, v3, v4
	v_mul_lo_u32 v6, v4, v2
	v_add_u32_e32 v8, 1, v3
	v_sub_u32_e32 v3, v3, v6
	v_add_u32_e32 v7, 1, v4
	v_cmp_ge_u32_e32 vcc, v3, v2
	v_sub_u32_e32 v6, v3, v2
	s_nop 0
	v_cndmask_b32_e32 v4, v4, v7, vcc
	v_cndmask_b32_e32 v3, v3, v6, vcc
	v_add_u32_e32 v6, 1, v4
	v_cmp_ge_u32_e32 vcc, v3, v2
	s_nop 1
	v_cndmask_b32_e32 v3, v4, v6, vcc
	v_mad_u64_u32 v[6:7], s[2:3], v2, v3, v[2:3]
	v_cmp_ne_u32_e32 vcc, v8, v6
	s_and_saveexec_b64 s[2:3], vcc
	s_xor_b64 s[2:3], exec, s[2:3]
	s_cbranch_execz .LBB0_103
	v_readlane_b32 s4, v254, 0
	v_add_u32_e32 v4, 0x260, v1
	v_readlane_b32 s5, v254, 1
	s_nop 1
	v_lshl_add_u64 v[0:1], v[4:5], 2, s[4:5]
	global_load_dword v2, v[0:1], off sc1
	s_waitcnt vmcnt(0)
	v_cmp_eq_u32_e32 vcc, v2, v3
	s_and_saveexec_b64 s[4:5], vcc
	s_cbranch_execz .LBB0_102
	s_mov_b64 s[6:7], 0

.LBB0_106:
	s_or_b64 exec, exec, s[4:5]
	v_cvt_f32_u32_e32 v4, v0
	s_waitcnt vmcnt(0)
	v_readfirstlane_b32 s2, v3
	v_rcp_iflag_f32_e32 v4, v4
	s_nop 0
	v_add_u32_e32 v2, s2, v2
	v_add_u32_e32 v6, 1, v2
	v_mul_f32_e32 v3, 0x4f7ffffe, v4
	v_cvt_u32_f32_e32 v3, v3
	v_sub_u32_e32 v4, 0, v0
	v_mul_lo_u32 v4, v4, v3
	v_mul_hi_u32 v4, v3, v4
	v_add_u32_e32 v3, v3, v4
	v_mul_hi_u32 v3, v2, v3
	v_mul_lo_u32 v4, v3, v0
	v_sub_u32_e32 v2, v2, v4
	v_add_u32_e32 v5, 1, v3
	v_cmp_ge_u32_e32 vcc, v2, v0
	v_sub_u32_e32 v4, v2, v0
	s_nop 0
	v_cndmask_b32_e32 v3, v3, v5, vcc
	v_cndmask_b32_e32 v2, v2, v4, vcc
	v_add_u32_e32 v4, 1, v3
	v_cmp_ge_u32_e32 vcc, v2, v0
	s_nop 1
	v_cndmask_b32_e32 v2, v3, v4, vcc
	v_mad_u64_u32 v[4:5], s[2:3], v0, v2, v[0:1]
	s_add_u32 s2, s52, 0xffffe00
	v_cmp_ne_u32_e32 vcc, v6, v4
	s_addc_u32 s3, s53, 0
	s_and_saveexec_b64 s[4:5], vcc
	s_xor_b64 s[4:5], exec, s[4:5]
	s_cbranch_execz .LBB0_111
	v_mov_b32_e32 v0, 0
	global_load_dword v3, v0, s[2:3] sc1
	s_waitcnt vmcnt(0)
	v_cmp_lt_u32_e32 vcc, v3, v4
	s_and_saveexec_b64 s[6:7], vcc
	s_cbranch_execz .LBB0_110
	s_mov_b64 s[8:9], 0
.LBB0_109:
	s_sleep 1
	global_load_dword v3, v0, s[2:3] sc1
	s_waitcnt vmcnt(0)
	v_cmp_ge_u32_e32 vcc, v3, v4
	s_or_b64 s[8:9], vcc, s[8:9]
	s_andn2_b64 exec, exec, s[8:9]
	s_cbranch_execnz .LBB0_109

.LBB0_111:
	s_andn2_saveexec_b64 s[4:5], s[4:5]
	s_cbranch_execz .LBB0_115
	s_mov_b64 s[8:9], exec
	v_mbcnt_lo_u32_b32 v0, s8, 0
	v_mbcnt_hi_u32_b32 v0, s9, v0
	v_cmp_eq_u32_e32 vcc, 0, v0
	s_and_saveexec_b64 s[6:7], vcc
	s_cbranch_execz .LBB0_114
	s_bcnt1_i32_b64 s8, s[8:9]
	v_mov_b32_e32 v0, 0
	v_mov_b32_e32 v2, s8
	s_nop 0

.LBB0_340:
	s_waitcnt vmcnt(0)
	v_mov_b32_e32 v0, v190
	s_waitcnt vmcnt(0)
	s_barrier
	s_nop 0
	v_cmp_eq_u32_e32 vcc, 0, v0
	s_and_saveexec_b64 s[38:39], vcc
	s_cbranch_execz .LBB0_365
	v_mov_b32_e32 v1, s101
	v_mov_b32_e32 v2, s99
	v_mov_b32_e32 v0, s100
	s_waitcnt lgkmcnt(0)
	v_cmp_eq_u32_e32 vcc, 0, v2
	s_and_saveexec_b64 s[40:41], vcc
	s_cbranch_execz .LBB0_347
	s_add_u32 s42, s52, 0xffff080
	s_addc_u32 s43, s53, 0
	s_add_u32 s44, s52, 0xffff100
	s_addc_u32 s45, s53, 0
	s_add_u32 s46, s52, 0xffff180
	s_addc_u32 s47, s53, 0
	s_add_u32 s50, s52, 0xffff200
	s_addc_u32 s51, s53, 0
	s_mov_b64 s[16:17], s[52:53]
	s_add_u32 s52, s16, 0xffff280
	s_addc_u32 s53, s17, 0
	s_add_u32 s54, s16, 0xffff300
	s_addc_u32 s55, s17, 0
	s_add_u32 s92, s16, 0xffff380
	s_addc_u32 s93, s17, 0
	s_add_u32 s48, s16, 0xffff400
	v_mov_b32_e32 v3, 0
	v_cmp_eq_u32_e64 s[2:3], 0, v1
	v_cmp_eq_u32_e64 s[4:5], 1, v1
	v_cmp_eq_u32_e64 s[6:7], 2, v1
	v_cmp_eq_u32_e64 s[8:9], 3, v1
	v_cmp_eq_u32_e64 s[10:11], 4, v1
	v_cmp_eq_u32_e64 s[12:13], 5, v1
	v_cmp_eq_u32_e64 s[14:15], 6, v1
	s_addc_u32 s49, s17, 0
	v_cmp_eq_u32_e64 s[16:17], 7, v1
	v_mov_b32_e32 v2, 0
	s_branch .LBB0_344

.LBB0_388:
	s_waitcnt vmcnt(0)
	v_mov_b32_e32 v0, v190
	s_barrier
	s_nop 0
	v_cmp_eq_u32_e32 vcc, 0, v0
	s_and_saveexec_b64 s[38:39], vcc
	s_load_dwordx16 s[16:31], s[0:1], 0x80
	s_cbranch_execz .LBB0_413
	v_mov_b32_e32 v1, s101
	v_mov_b32_e32 v2, s99
	v_mov_b32_e32 v0, s100
	s_waitcnt lgkmcnt(0)
	v_cmp_eq_u32_e32 vcc, 0, v2
	s_and_saveexec_b64 s[40:41], vcc
	s_cbranch_execz .LBB0_395
	s_add_u32 s42, s52, 0xffff080
	s_addc_u32 s43, s53, 0
	s_add_u32 s44, s52, 0xffff100
	s_addc_u32 s45, s53, 0
	s_add_u32 s46, s52, 0xffff180
	s_addc_u32 s47, s53, 0
	s_add_u32 s50, s52, 0xffff200
	s_addc_u32 s51, s53, 0
	s_mov_b64 s[16:17], s[52:53]
	s_add_u32 s52, s16, 0xffff280
	s_addc_u32 s53, s17, 0
	s_add_u32 s54, s16, 0xffff300
	s_addc_u32 s55, s17, 0
	s_add_u32 s92, s16, 0xffff380
	s_addc_u32 s93, s17, 0
	s_add_u32 s48, s16, 0xffff400
	v_mov_b32_e32 v3, 0
	v_cmp_eq_u32_e64 s[2:3], 0, v1
	v_cmp_eq_u32_e64 s[4:5], 1, v1
	v_cmp_eq_u32_e64 s[6:7], 2, v1
	v_cmp_eq_u32_e64 s[8:9], 3, v1
	v_cmp_eq_u32_e64 s[10:11], 4, v1
	v_cmp_eq_u32_e64 s[12:13], 5, v1
	v_cmp_eq_u32_e64 s[14:15], 6, v1
	s_addc_u32 s49, s17, 0
	v_cmp_eq_u32_e64 s[16:17], 7, v1
	v_mov_b32_e32 v2, 0
	s_branch .LBB0_392

.LBB0_403:
	s_or_b64 exec, exec, s[4:5]
	s_waitcnt vmcnt(0)
	v_readfirstlane_b32 s2, v3
	v_sub_u32_e32 v4, 0, v0
	s_nop 0
	v_add_u32_e32 v3, s2, v2
	v_cvt_f32_u32_e32 v2, v0
	v_rcp_iflag_f32_e32 v2, v2
	s_nop 0
	v_mul_f32_e32 v2, 0x4f7ffffe, v2
	v_cvt_u32_f32_e32 v2, v2
	v_mul_lo_u32 v4, v4, v2
	v_mul_hi_u32 v4, v2, v4
	v_add_u32_e32 v2, v2, v4
	v_mul_hi_u32 v2, v3, v2
	v_mul_lo_u32 v4, v2, v0
	v_sub_u32_e32 v4, v3, v4
	v_cmp_ge_u32_e32 vcc, v4, v0
	v_add_u32_e32 v5, 1, v2
	v_add_u32_e32 v3, 1, v3
	v_cndmask_b32_e32 v2, v2, v5, vcc
	v_sub_u32_e32 v5, v4, v0
	v_cndmask_b32_e32 v4, v4, v5, vcc
	v_cmp_ge_u32_e32 vcc, v4, v0
	v_add_u32_e32 v4, 1, v2
	s_nop 0
	v_cndmask_b32_e32 v2, v2, v4, vcc
	v_mad_u64_u32 v[4:5], s[2:3], v0, v2, v[0:1]
	s_add_u32 s2, s52, 0xffffe00
	v_cmp_ne_u32_e32 vcc, v3, v4
	s_addc_u32 s3, s53, 0
	s_and_saveexec_b64 s[4:5], vcc
	s_xor_b64 s[4:5], exec, s[4:5]
	s_cbranch_execz .LBB0_408
	v_mov_b32_e32 v0, 0
	global_load_dword v3, v0, s[2:3] sc1
	s_waitcnt vmcnt(0)
	v_cmp_lt_u32_e32 vcc, v3, v4
	s_and_saveexec_b64 s[6:7], vcc
	s_cbranch_execz .LBB0_407
	s_mov_b64 s[8:9], 0

.LBB0_491:
	s_waitcnt vmcnt(0)
	v_mov_b32_e32 v0, v190
	s_waitcnt lgkmcnt(0)
	s_barrier
	s_nop 0
	v_cmp_eq_u32_e32 vcc, 0, v0
	s_and_saveexec_b64 s[38:39], vcc
	s_cbranch_execz .LBB0_516
	v_mov_b32_e32 v1, s101
	v_mov_b32_e32 v2, s99
	v_mov_b32_e32 v0, s100
	s_waitcnt lgkmcnt(0)
	v_cmp_eq_u32_e32 vcc, 0, v2
	s_and_saveexec_b64 s[40:41], vcc
	s_cbranch_execz .LBB0_498
	s_add_u32 s42, s52, 0xffff080
	s_addc_u32 s43, s53, 0
	s_add_u32 s44, s52, 0xffff100
	s_addc_u32 s45, s53, 0
	s_add_u32 s46, s52, 0xffff180
	s_addc_u32 s47, s53, 0
	s_add_u32 s50, s52, 0xffff200
	s_addc_u32 s51, s53, 0
	s_mov_b64 s[16:17], s[52:53]
	s_add_u32 s52, s16, 0xffff280
	s_addc_u32 s53, s17, 0
	s_add_u32 s54, s16, 0xffff300
	s_addc_u32 s55, s17, 0
	s_add_u32 s92, s16, 0xffff380
	s_addc_u32 s93, s17, 0
	s_add_u32 s48, s16, 0xffff400
	v_mov_b32_e32 v3, 0
	v_cmp_eq_u32_e64 s[2:3], 0, v1
	v_cmp_eq_u32_e64 s[4:5], 1, v1
	v_cmp_eq_u32_e64 s[6:7], 2, v1
	v_cmp_eq_u32_e64 s[8:9], 3, v1
	v_cmp_eq_u32_e64 s[10:11], 4, v1
	v_cmp_eq_u32_e64 s[12:13], 5, v1
	v_cmp_eq_u32_e64 s[14:15], 6, v1
	s_addc_u32 s49, s17, 0
	v_cmp_eq_u32_e64 s[16:17], 7, v1
	v_mov_b32_e32 v2, 0
	s_branch .LBB0_495

.LBB0_600:
	s_or_b64 exec, exec, s[4:5]
	s_waitcnt vmcnt(0)
	v_mov_b32_e32 v0, v190
	s_barrier
	s_nop 0
	v_cmp_eq_u32_e32 vcc, 0, v0
	s_and_saveexec_b64 s[38:39], vcc
	s_cbranch_execz .LBB0_625
	v_mov_b32_e32 v1, s101
	v_mov_b32_e32 v2, s99
	v_mov_b32_e32 v0, s100
	s_waitcnt lgkmcnt(0)
	v_cmp_eq_u32_e32 vcc, 0, v2
	s_and_saveexec_b64 s[40:41], vcc
	s_cbranch_execz .LBB0_607
	s_add_u32 s42, s52, 0xffff080
	s_addc_u32 s43, s53, 0
	s_add_u32 s44, s52, 0xffff100
	s_addc_u32 s45, s53, 0
	s_add_u32 s46, s52, 0xffff180
	s_addc_u32 s47, s53, 0
	s_mov_b64 s[16:17], s[52:53]
	s_add_u32 s52, s16, 0xffff200
	s_addc_u32 s53, s17, 0
	s_add_u32 s54, s16, 0xffff280
	s_addc_u32 s55, s17, 0
	s_add_u32 s92, s16, 0xffff300
	s_addc_u32 s93, s17, 0
	s_add_u32 s48, s16, 0xffff380
	s_addc_u32 s49, s17, 0
	s_add_u32 s50, s16, 0xffff400
	v_mov_b32_e32 v3, 0
	v_cmp_eq_u32_e64 s[2:3], 0, v1
	v_cmp_eq_u32_e64 s[4:5], 1, v1
	v_cmp_eq_u32_e64 s[6:7], 2, v1
	v_cmp_eq_u32_e64 s[8:9], 3, v1
	v_cmp_eq_u32_e64 s[10:11], 4, v1
	v_cmp_eq_u32_e64 s[12:13], 5, v1
	v_cmp_eq_u32_e64 s[14:15], 6, v1
	s_addc_u32 s51, s17, 0
	v_cmp_eq_u32_e64 s[16:17], 7, v1
	v_mov_b32_e32 v2, 0
	s_branch .LBB0_604

.LBB0_755:
	s_waitcnt vmcnt(0)
	v_mov_b32_e32 v0, v190
	s_waitcnt lgkmcnt(0)
	s_barrier
	s_nop 0
	v_cmp_eq_u32_e32 vcc, 0, v0
	s_and_saveexec_b64 s[38:39], vcc
	v_readlane_b32 s72, v254, 52
	v_readlane_b32 s73, v254, 53
	s_cbranch_execz .LBB0_780
	v_mov_b32_e32 v1, s101
	v_mov_b32_e32 v2, s99
	v_mov_b32_e32 v0, s100
	s_waitcnt lgkmcnt(0)
	v_cmp_eq_u32_e32 vcc, 0, v2
	s_and_saveexec_b64 s[40:41], vcc
	s_cbranch_execz .LBB0_762
	s_add_u32 s42, s52, 0xffff080
	s_addc_u32 s43, s53, 0
	s_add_u32 s44, s52, 0xffff100
	s_addc_u32 s45, s53, 0
	s_add_u32 s46, s52, 0xffff180
	s_addc_u32 s47, s53, 0
	s_mov_b64 s[16:17], s[52:53]
	s_add_u32 s52, s16, 0xffff200
	s_addc_u32 s53, s17, 0
	s_add_u32 s54, s16, 0xffff280
	s_addc_u32 s55, s17, 0
	s_add_u32 s92, s16, 0xffff300
	s_addc_u32 s93, s17, 0
	s_add_u32 s48, s16, 0xffff380
	s_addc_u32 s49, s17, 0
	s_add_u32 s50, s16, 0xffff400
	v_mov_b32_e32 v3, 0
	v_cmp_eq_u32_e64 s[2:3], 0, v1
	v_cmp_eq_u32_e64 s[4:5], 1, v1
	v_cmp_eq_u32_e64 s[6:7], 2, v1
	v_cmp_eq_u32_e64 s[8:9], 3, v1
	v_cmp_eq_u32_e64 s[10:11], 4, v1
	v_cmp_eq_u32_e64 s[12:13], 5, v1
	v_cmp_eq_u32_e64 s[14:15], 6, v1
	s_addc_u32 s51, s17, 0
	v_cmp_eq_u32_e64 s[16:17], 7, v1
	v_mov_b32_e32 v2, 0
	s_branch .LBB0_759

.LBB0_795:
	s_or_b64 exec, exec, s[6:7]
	s_waitcnt vmcnt(0)
	v_mov_b32_e32 v0, v190
	s_barrier
	s_nop 0
	v_cmp_eq_u32_e32 vcc, 0, v0
	s_and_saveexec_b64 s[36:37], vcc
	s_cbranch_execz .LBB0_820
	v_mov_b32_e32 v1, s101
	v_mov_b32_e32 v2, s99
	v_mov_b32_e32 v0, s100
	s_waitcnt lgkmcnt(0)
	v_cmp_eq_u32_e32 vcc, 0, v2
	s_and_saveexec_b64 s[38:39], vcc
	s_cbranch_execz .LBB0_802
	s_add_u32 s40, s52, 0xffff080
	s_addc_u32 s41, s53, 0
	s_add_u32 s42, s52, 0xffff100
	s_addc_u32 s43, s53, 0
	s_add_u32 s44, s52, 0xffff180
	s_addc_u32 s45, s53, 0
	s_add_u32 s46, s52, 0xffff200
	s_addc_u32 s47, s53, 0
	s_add_u32 s48, s52, 0xffff280
	s_addc_u32 s49, s53, 0
	s_add_u32 s50, s52, 0xffff300
	s_addc_u32 s51, s53, 0
	s_mov_b64 s[14:15], s[52:53]
	s_add_u32 s52, s14, 0xffff380
	s_addc_u32 s53, s15, 0
	s_add_u32 s54, s14, 0xffff400
	v_mov_b32_e32 v3, 0
	v_cmp_eq_u32_e64 s[0:1], 0, v1
	v_cmp_eq_u32_e64 s[2:3], 1, v1
	v_cmp_eq_u32_e64 s[4:5], 2, v1
	v_cmp_eq_u32_e64 s[6:7], 3, v1
	v_cmp_eq_u32_e64 s[8:9], 4, v1
	v_cmp_eq_u32_e64 s[10:11], 5, v1
	v_cmp_eq_u32_e64 s[12:13], 6, v1
	s_addc_u32 s55, s15, 0
	v_cmp_eq_u32_e64 s[14:15], 7, v1
	v_mov_b32_e32 v2, 0
	s_branch .LBB0_799

.LBB0_810:
	s_or_b64 exec, exec, s[2:3]
	s_waitcnt vmcnt(0)
	v_readfirstlane_b32 s0, v3
	v_sub_u32_e32 v4, 0, v0
	s_nop 0
	v_add_u32_e32 v3, s0, v2
	v_cvt_f32_u32_e32 v2, v0
	v_rcp_iflag_f32_e32 v2, v2
	s_nop 0
	v_mul_f32_e32 v2, 0x4f7ffffe, v2
	v_cvt_u32_f32_e32 v2, v2
	v_mul_lo_u32 v4, v4, v2
	v_mul_hi_u32 v4, v2, v4
	v_add_u32_e32 v2, v2, v4
	v_mul_hi_u32 v2, v3, v2
	v_mul_lo_u32 v4, v2, v0
	v_sub_u32_e32 v4, v3, v4
	v_cmp_ge_u32_e32 vcc, v4, v0
	v_add_u32_e32 v5, 1, v2
	v_add_u32_e32 v3, 1, v3
	v_cndmask_b32_e32 v2, v2, v5, vcc
	v_sub_u32_e32 v5, v4, v0
	v_cndmask_b32_e32 v4, v4, v5, vcc
	v_cmp_ge_u32_e32 vcc, v4, v0
	v_add_u32_e32 v4, 1, v2
	s_nop 0
	v_cndmask_b32_e32 v2, v2, v4, vcc
	v_mad_u64_u32 v[4:5], s[0:1], v0, v2, v[0:1]
	s_add_u32 s0, s52, 0xffffe00
	v_cmp_ne_u32_e32 vcc, v3, v4
	s_addc_u32 s1, s53, 0
	s_and_saveexec_b64 s[2:3], vcc
	s_xor_b64 s[2:3], exec, s[2:3]
	s_cbranch_execz .LBB0_815
	v_mov_b32_e32 v0, 0
	global_load_dword v3, v0, s[0:1] sc1
	s_waitcnt vmcnt(0)
	v_cmp_lt_u32_e32 vcc, v3, v4
	s_and_saveexec_b64 s[4:5], vcc
	s_cbranch_execz .LBB0_814
	s_mov_b64 s[6:7], 0
.LBB0_813:
	s_sleep 1
	global_load_dword v3, v0, s[0:1] sc1
	s_waitcnt vmcnt(0)
	v_cmp_ge_u32_e32 vcc, v3, v4
	s_or_b64 s[6:7], vcc, s[6:7]
	s_andn2_b64 exec, exec, s[6:7]
	s_cbranch_execnz .LBB0_813

.LBB0_815:
	s_andn2_saveexec_b64 s[2:3], s[2:3]
	s_cbranch_execz .LBB0_819
	s_mov_b64 s[6:7], exec
	v_mbcnt_lo_u32_b32 v0, s6, 0
	v_mbcnt_hi_u32_b32 v0, s7, v0
	v_cmp_eq_u32_e32 vcc, 0, v0
	s_and_saveexec_b64 s[4:5], vcc
	s_cbranch_execz .LBB0_818
	s_bcnt1_i32_b64 s6, s[6:7]
	v_mov_b32_e32 v0, 0
	v_mov_b32_e32 v2, s6
	s_nop 0

.LBB0_831:
	s_waitcnt vmcnt(0)
	v_mov_b32_e32 v0, v190
	s_barrier
	s_nop 0
	v_cmp_eq_u32_e32 vcc, 0, v0
	s_and_saveexec_b64 s[40:41], vcc
	s_cbranch_execz .LBB0_856
	v_mov_b32_e32 v1, s101
	v_mov_b32_e32 v2, s99
	v_mov_b32_e32 v0, s100
	s_waitcnt lgkmcnt(0)
	v_cmp_eq_u32_e32 vcc, 0, v2
	s_and_saveexec_b64 s[42:43], vcc
	s_cbranch_execz .LBB0_838
	s_add_u32 s44, s52, 0xffff080
	s_addc_u32 s45, s53, 0
	s_add_u32 s46, s52, 0xffff100
	s_addc_u32 s47, s53, 0
	s_add_u32 s48, s52, 0xffff180
	s_addc_u32 s49, s53, 0
	s_add_u32 s50, s52, 0xffff200
	s_addc_u32 s51, s53, 0
	s_add_u32 s38, s52, 0xffff280
	s_addc_u32 s39, s53, 0
	s_add_u32 s36, s52, 0xffff300
	s_addc_u32 s37, s53, 0
	s_mov_b64 s[14:15], s[52:53]
	s_add_u32 s52, s14, 0xffff380
	s_addc_u32 s53, s15, 0
	s_add_u32 s54, s14, 0xffff400
	v_mov_b32_e32 v3, 0
	v_cmp_eq_u32_e64 s[0:1], 0, v1
	v_cmp_eq_u32_e64 s[2:3], 1, v1
	v_cmp_eq_u32_e64 s[4:5], 2, v1
	v_cmp_eq_u32_e64 s[6:7], 3, v1
	v_cmp_eq_u32_e64 s[8:9], 4, v1
	v_cmp_eq_u32_e64 s[10:11], 5, v1
	v_cmp_eq_u32_e64 s[12:13], 6, v1
	s_addc_u32 s55, s15, 0
	v_cmp_eq_u32_e64 s[14:15], 7, v1
	v_mov_b32_e32 v2, 0
	s_branch .LBB0_835

.LBB0_859:
	s_or_b64 exec, exec, s[0:1]
	s_waitcnt vmcnt(0)
	v_mov_b32_e32 v0, v190
	s_barrier
	s_nop 0
	v_cmp_eq_u32_e32 vcc, 0, v0
	s_and_saveexec_b64 s[40:41], vcc
	s_cbranch_execz .LBB0_884
	v_mov_b32_e32 v1, s101
	v_mov_b32_e32 v2, s99
	v_mov_b32_e32 v0, s100
	s_waitcnt lgkmcnt(0)
	v_cmp_eq_u32_e32 vcc, 0, v2
	s_and_saveexec_b64 s[42:43], vcc
	s_cbranch_execz .LBB0_866
	s_add_u32 s44, s52, 0xffff080
	s_addc_u32 s45, s53, 0
	s_add_u32 s46, s52, 0xffff100
	s_addc_u32 s47, s53, 0
	s_add_u32 s48, s52, 0xffff180
	s_addc_u32 s49, s53, 0
	s_add_u32 s50, s52, 0xffff200
	s_addc_u32 s51, s53, 0
	s_add_u32 s38, s52, 0xffff280
	s_addc_u32 s39, s53, 0
	s_add_u32 s36, s52, 0xffff300
	s_addc_u32 s37, s53, 0
	s_mov_b64 s[14:15], s[52:53]
	s_add_u32 s52, s14, 0xffff380
	s_addc_u32 s53, s15, 0
	s_add_u32 s54, s14, 0xffff400
	v_mov_b32_e32 v3, 0
	v_cmp_eq_u32_e64 s[0:1], 0, v1
	v_cmp_eq_u32_e64 s[2:3], 1, v1
	v_cmp_eq_u32_e64 s[4:5], 2, v1
	v_cmp_eq_u32_e64 s[6:7], 3, v1
	v_cmp_eq_u32_e64 s[8:9], 4, v1
	v_cmp_eq_u32_e64 s[10:11], 5, v1
	v_cmp_eq_u32_e64 s[12:13], 6, v1
	s_addc_u32 s55, s15, 0
	v_cmp_eq_u32_e64 s[14:15], 7, v1
	v_mov_b32_e32 v2, 0
	s_branch .LBB0_863

.LBB0_895:
	s_waitcnt vmcnt(0)
	v_mov_b32_e32 v0, v190
	s_waitcnt vmcnt(0)
	s_barrier
	s_nop 0
	v_cmp_eq_u32_e32 vcc, 0, v0
	s_and_saveexec_b64 s[42:43], vcc
	s_cbranch_execz .LBB0_920
	v_mov_b32_e32 v1, s101
	v_mov_b32_e32 v2, s99
	v_mov_b32_e32 v0, s100
	s_waitcnt lgkmcnt(0)
	v_cmp_eq_u32_e32 vcc, 0, v2
	s_and_saveexec_b64 s[44:45], vcc
	s_cbranch_execz .LBB0_902
	s_add_u32 s46, s52, 0xffff080
	s_addc_u32 s47, s53, 0
	s_add_u32 s48, s52, 0xffff100
	s_addc_u32 s49, s53, 0
	s_add_u32 s50, s52, 0xffff180
	s_addc_u32 s51, s53, 0
	s_add_u32 s54, s52, 0xffff200
	s_addc_u32 s55, s53, 0
	s_add_u32 s38, s52, 0xffff280
	s_addc_u32 s39, s53, 0
	s_add_u32 s36, s52, 0xffff300
	s_addc_u32 s37, s53, 0
	s_add_u32 s74, s52, 0xffff380
	s_addc_u32 s75, s53, 0
	s_add_u32 s52, s52, 0xffff400
	v_mov_b32_e32 v3, 0
	v_cmp_eq_u32_e64 s[0:1], 0, v1
	v_cmp_eq_u32_e64 s[2:3], 1, v1
	v_cmp_eq_u32_e64 s[4:5], 2, v1
	v_cmp_eq_u32_e64 s[6:7], 3, v1
	v_cmp_eq_u32_e64 s[8:9], 4, v1
	v_cmp_eq_u32_e64 s[10:11], 5, v1
	v_cmp_eq_u32_e64 s[12:13], 6, v1
	s_addc_u32 s53, s53, 0
	v_cmp_eq_u32_e64 s[14:15], 7, v1
	v_mov_b32_e32 v2, 0
	s_branch .LBB0_899

.LBB0_996:
	s_waitcnt vmcnt(0)
	v_mov_b32_e32 v0, v190
	s_waitcnt lgkmcnt(0)
	s_barrier
	s_nop 0
	v_cmp_eq_u32_e32 vcc, 0, v0
	s_and_saveexec_b64 s[46:47], vcc
	s_cbranch_execz .LBB0_1021
	v_mov_b32_e32 v1, s101
	v_mov_b32_e32 v2, s99
	v_mov_b32_e32 v0, s100
	s_waitcnt lgkmcnt(0)
	v_cmp_eq_u32_e32 vcc, 0, v2
	s_and_saveexec_b64 s[74:75], vcc
	s_cbranch_execz .LBB0_1003
	s_add_u32 s48, s52, 0xffff080
	s_addc_u32 s49, s53, 0
	s_add_u32 s50, s52, 0xffff100
	s_addc_u32 s51, s53, 0
	s_add_u32 s92, s52, 0xffff180
	s_addc_u32 s93, s53, 0
	s_add_u32 s38, s52, 0xffff200
	s_addc_u32 s39, s53, 0
	s_add_u32 s36, s52, 0xffff280
	s_addc_u32 s37, s53, 0
	s_add_u32 s44, s52, 0xffff300
	s_addc_u32 s45, s53, 0
	s_mov_b64 s[14:15], s[52:53]
	s_add_u32 s52, s14, 0xffff380
	s_addc_u32 s53, s15, 0
	s_add_u32 s76, s14, 0xffff400
	v_mov_b32_e32 v3, 0
	v_cmp_eq_u32_e64 s[0:1], 0, v1
	v_cmp_eq_u32_e64 s[2:3], 1, v1
	v_cmp_eq_u32_e64 s[4:5], 2, v1
	v_cmp_eq_u32_e64 s[6:7], 3, v1
	v_cmp_eq_u32_e64 s[8:9], 4, v1
	v_cmp_eq_u32_e64 s[10:11], 5, v1
	v_cmp_eq_u32_e64 s[12:13], 6, v1
	s_addc_u32 s77, s15, 0
	v_cmp_eq_u32_e64 s[14:15], 7, v1
	v_mov_b32_e32 v2, 0
	s_branch .LBB0_1000

.LBB0_1107:
	s_waitcnt vmcnt(0)
	v_mov_b32_e32 v0, v190
	s_barrier
	s_nop 0
	v_cmp_eq_u32_e32 vcc, 0, v0
	s_and_saveexec_b64 s[0:1], vcc
	s_cbranch_execz .LBB0_1132
	v_mov_b32_e32 v1, s101
	v_mov_b32_e32 v2, s99
	v_mov_b32_e32 v0, s100
	s_waitcnt lgkmcnt(0)
	v_cmp_eq_u32_e32 vcc, 0, v2
	s_and_saveexec_b64 s[46:47], vcc
	s_cbranch_execz .LBB0_1114
	s_add_u32 s48, s52, 0xffff080
	s_addc_u32 s49, s53, 0
	s_add_u32 s50, s52, 0xffff100
	s_addc_u32 s51, s53, 0
	s_mov_b64 s[16:17], s[52:53]
	s_add_u32 s52, s16, 0xffff180
	s_addc_u32 s53, s17, 0
	s_add_u32 s38, s16, 0xffff200
	s_addc_u32 s39, s17, 0
	s_add_u32 s54, s16, 0xffff280
	s_addc_u32 s55, s17, 0
	s_add_u32 s44, s16, 0xffff300
	s_addc_u32 s45, s17, 0
	s_add_u32 s66, s16, 0xffff380
	s_addc_u32 s67, s17, 0
	s_add_u32 s68, s16, 0xffff400
	v_mov_b32_e32 v3, 0
	v_cmp_eq_u32_e64 s[2:3], 0, v1
	v_cmp_eq_u32_e64 s[4:5], 1, v1
	v_cmp_eq_u32_e64 s[6:7], 2, v1
	v_cmp_eq_u32_e64 s[8:9], 3, v1
	v_cmp_eq_u32_e64 s[10:11], 4, v1
	v_cmp_eq_u32_e64 s[12:13], 5, v1
	v_cmp_eq_u32_e64 s[14:15], 6, v1
	s_addc_u32 s69, s17, 0
	v_cmp_eq_u32_e64 s[16:17], 7, v1
	v_mov_b32_e32 v2, 0
	s_branch .LBB0_1111

.LBB0_1231:
	s_waitcnt vmcnt(0)
	v_mov_b32_e32 v0, v190
	s_waitcnt lgkmcnt(0)
	s_barrier
	s_nop 0
	v_cmp_eq_u32_e32 vcc, 0, v0
	s_and_saveexec_b64 s[0:1], vcc
	s_cbranch_execz .LBB0_1256
	v_mov_b32_e32 v1, s101
	v_mov_b32_e32 v2, s99
	v_mov_b32_e32 v0, s100
	s_waitcnt lgkmcnt(0)
	v_cmp_eq_u32_e32 vcc, 0, v2
	s_and_saveexec_b64 s[40:41], vcc
	s_cbranch_execz .LBB0_1238
	v_readlane_b32 s16, v254, 58
	v_readlane_b32 s17, v254, 59
	s_add_u32 s42, s16, 0xffff080
	s_addc_u32 s43, s17, 0
	s_add_u32 s44, s16, 0xffff100
	s_addc_u32 s45, s17, 0
	s_add_u32 s46, s16, 0xffff180
	s_addc_u32 s47, s17, 0
	s_add_u32 s38, s16, 0xffff200
	s_addc_u32 s39, s17, 0
	s_add_u32 s48, s16, 0xffff280
	s_addc_u32 s49, s17, 0
	s_add_u32 s50, s16, 0xffff300
	s_addc_u32 s51, s17, 0
	s_add_u32 s54, s16, 0xffff380
	s_addc_u32 s55, s17, 0
	s_add_u32 s66, s16, 0xffff400
	v_mov_b32_e32 v3, 0
	v_cmp_eq_u32_e64 s[2:3], 0, v1
	v_cmp_eq_u32_e64 s[4:5], 1, v1
	v_cmp_eq_u32_e64 s[6:7], 2, v1
	v_cmp_eq_u32_e64 s[8:9], 3, v1
	v_cmp_eq_u32_e64 s[10:11], 4, v1
	v_cmp_eq_u32_e64 s[12:13], 5, v1
	v_cmp_eq_u32_e64 s[14:15], 6, v1
	s_addc_u32 s67, s17, 0
	v_cmp_eq_u32_e64 s[16:17], 7, v1
	v_mov_b32_e32 v2, 0
	s_branch .LBB0_1235

.LBB0_1246:
	s_or_b64 exec, exec, s[4:5]
	v_cvt_f32_u32_e32 v4, v0
	s_waitcnt vmcnt(0)
	v_readfirstlane_b32 s2, v3
	v_rcp_iflag_f32_e32 v4, v4
	s_nop 0
	v_add_u32_e32 v2, s2, v2
	v_add_u32_e32 v6, 1, v2
	v_mul_f32_e32 v3, 0x4f7ffffe, v4
	v_cvt_u32_f32_e32 v3, v3
	v_sub_u32_e32 v4, 0, v0
	v_mul_lo_u32 v4, v4, v3
	v_mul_hi_u32 v4, v3, v4
	v_add_u32_e32 v3, v3, v4
	v_mul_hi_u32 v3, v2, v3
	v_mul_lo_u32 v4, v3, v0
	v_sub_u32_e32 v2, v2, v4
	v_add_u32_e32 v5, 1, v3
	v_cmp_ge_u32_e32 vcc, v2, v0
	v_sub_u32_e32 v4, v2, v0
	s_nop 0
	v_cndmask_b32_e32 v3, v3, v5, vcc
	v_cndmask_b32_e32 v2, v2, v4, vcc
	v_add_u32_e32 v4, 1, v3
	v_cmp_ge_u32_e32 vcc, v2, v0
	s_nop 1
	v_cndmask_b32_e32 v2, v3, v4, vcc
	v_mad_u64_u32 v[4:5], s[2:3], v0, v2, v[0:1]
	v_readlane_b32 s2, v254, 58
	v_readlane_b32 s3, v254, 59
	s_add_u32 s2, s2, 0xffffe00
	v_cmp_ne_u32_e32 vcc, v6, v4
	s_addc_u32 s3, s3, 0
	s_and_saveexec_b64 s[4:5], vcc
	s_xor_b64 s[4:5], exec, s[4:5]
	s_cbranch_execz .LBB0_1251
	v_mov_b32_e32 v0, 0
	global_load_dword v3, v0, s[2:3] sc1
	s_waitcnt vmcnt(0)
	v_cmp_lt_u32_e32 vcc, v3, v4
	s_and_saveexec_b64 s[6:7], vcc
	s_cbranch_execz .LBB0_1250
	s_mov_b64 s[8:9], 0

.LBB0_1264:
	s_waitcnt vmcnt(0)
	v_mov_b32_e32 v0, v190
	s_barrier
	s_nop 0
	v_cmp_eq_u32_e32 vcc, 0, v0
	s_and_saveexec_b64 s[0:1], vcc
	v_readlane_b32 s52, v254, 58
	v_readlane_b32 s53, v254, 59
	s_cbranch_execz .LBB0_1289
	v_mov_b32_e32 v1, s101
	v_mov_b32_e32 v2, s99
	v_mov_b32_e32 v0, s100
	s_waitcnt lgkmcnt(0)
	v_cmp_eq_u32_e32 vcc, 0, v2
	s_and_saveexec_b64 s[2:3], vcc
	s_cbranch_execz .LBB0_1271
	s_add_u32 s40, s52, 0xffff080
	s_addc_u32 s41, s53, 0
	s_add_u32 s42, s52, 0xffff100
	s_addc_u32 s43, s53, 0
	s_add_u32 s44, s52, 0xffff180
	s_addc_u32 s45, s53, 0
	s_add_u32 s46, s52, 0xffff200
	s_addc_u32 s47, s53, 0
	s_add_u32 s48, s52, 0xffff280
	s_addc_u32 s49, s53, 0
	s_add_u32 s50, s52, 0xffff300
	s_addc_u32 s51, s53, 0
	s_mov_b64 s[18:19], s[52:53]
	s_add_u32 s52, s18, 0xffff380
	s_addc_u32 s53, s19, 0
	s_add_u32 s54, s18, 0xffff400
	v_mov_b32_e32 v3, 0
	v_cmp_eq_u32_e64 s[4:5], 0, v1
	v_cmp_eq_u32_e64 s[6:7], 1, v1
	v_cmp_eq_u32_e64 s[8:9], 2, v1
	v_cmp_eq_u32_e64 s[10:11], 3, v1
	v_cmp_eq_u32_e64 s[12:13], 4, v1
	v_cmp_eq_u32_e64 s[14:15], 5, v1
	v_cmp_eq_u32_e64 s[16:17], 6, v1
	s_addc_u32 s55, s19, 0
	v_cmp_eq_u32_e64 s[18:19], 7, v1
	v_mov_b32_e32 v2, 0
	s_branch .LBB0_1268

.LBB0_1292:
	s_or_b64 exec, exec, s[0:1]
	s_waitcnt vmcnt(0)
	v_mov_b32_e32 v0, v190
	s_barrier
	s_nop 0
	v_cmp_eq_u32_e32 vcc, 0, v0
	s_and_saveexec_b64 s[0:1], vcc
	s_cbranch_execz .LBB0_1317
	v_mov_b32_e32 v1, s101
	v_mov_b32_e32 v2, s99
	v_mov_b32_e32 v0, s100
	s_waitcnt lgkmcnt(0)
	v_cmp_eq_u32_e32 vcc, 0, v2
	s_and_saveexec_b64 s[2:3], vcc
	s_cbranch_execz .LBB0_1299
	s_add_u32 s40, s52, 0xffff080
	s_addc_u32 s41, s53, 0
	s_add_u32 s42, s52, 0xffff100
	s_addc_u32 s43, s53, 0
	s_add_u32 s44, s52, 0xffff180
	s_addc_u32 s45, s53, 0
	s_add_u32 s46, s52, 0xffff200
	s_addc_u32 s47, s53, 0
	s_add_u32 s48, s52, 0xffff280
	s_addc_u32 s49, s53, 0
	s_add_u32 s50, s52, 0xffff300
	s_addc_u32 s51, s53, 0
	s_mov_b64 s[18:19], s[52:53]
	s_add_u32 s52, s18, 0xffff380
	s_addc_u32 s53, s19, 0
	s_add_u32 s54, s18, 0xffff400
	v_mov_b32_e32 v3, 0
	v_cmp_eq_u32_e64 s[4:5], 0, v1
	v_cmp_eq_u32_e64 s[6:7], 1, v1
	v_cmp_eq_u32_e64 s[8:9], 2, v1
	v_cmp_eq_u32_e64 s[10:11], 3, v1
	v_cmp_eq_u32_e64 s[12:13], 4, v1
	v_cmp_eq_u32_e64 s[14:15], 5, v1
	v_cmp_eq_u32_e64 s[16:17], 6, v1
	s_addc_u32 s55, s19, 0
	v_cmp_eq_u32_e64 s[18:19], 7, v1
	v_mov_b32_e32 v2, 0
	s_branch .LBB0_1296

.LBB0_1409:
	s_waitcnt vmcnt(0)
	v_mov_b32_e32 v0, v190
	s_waitcnt vmcnt(0)
	s_barrier
	s_nop 0
	v_cmp_eq_u32_e32 vcc, 0, v0
	s_and_saveexec_b64 s[0:1], vcc
	s_cbranch_execz .LBB0_1434
	v_mov_b32_e32 v1, s101
	v_mov_b32_e32 v2, s99
	v_mov_b32_e32 v0, s100
	s_waitcnt lgkmcnt(0)
	v_cmp_eq_u32_e32 vcc, 0, v2
	s_and_saveexec_b64 s[2:3], vcc
	s_cbranch_execz .LBB0_1416
	s_add_u32 s44, s52, 0xffff080
	s_addc_u32 s45, s53, 0
	s_add_u32 s46, s52, 0xffff100
	s_addc_u32 s47, s53, 0
	s_add_u32 s48, s52, 0xffff180
	s_addc_u32 s49, s53, 0
	s_add_u32 s50, s52, 0xffff200
	s_addc_u32 s51, s53, 0
	s_mov_b64 s[18:19], s[52:53]
	s_add_u32 s52, s18, 0xffff280
	s_addc_u32 s53, s19, 0
	s_add_u32 s54, s18, 0xffff300
	s_addc_u32 s55, s19, 0
	s_add_u32 s66, s18, 0xffff380
	s_addc_u32 s67, s19, 0
	s_add_u32 s74, s18, 0xffff400
	v_mov_b32_e32 v3, 0
	v_cmp_eq_u32_e64 s[4:5], 0, v1
	v_cmp_eq_u32_e64 s[6:7], 1, v1
	v_cmp_eq_u32_e64 s[8:9], 2, v1
	v_cmp_eq_u32_e64 s[10:11], 3, v1
	v_cmp_eq_u32_e64 s[12:13], 4, v1
	v_cmp_eq_u32_e64 s[14:15], 5, v1
	v_cmp_eq_u32_e64 s[16:17], 6, v1
	s_addc_u32 s75, s19, 0
	v_cmp_eq_u32_e64 s[18:19], 7, v1
	v_mov_b32_e32 v2, 0
	s_branch .LBB0_1413

.LBB0_1481:
	s_waitcnt vmcnt(0)
	v_mov_b32_e32 v0, v190
	s_waitcnt vmcnt(63) expcnt(7) lgkmcnt(15)
	s_barrier
	s_nop 0
	v_cmp_eq_u32_e32 vcc, 0, v0
	s_and_saveexec_b64 s[0:1], vcc
	s_cbranch_execz .LBB0_1506
	v_mov_b32_e32 v1, s101
	v_mov_b32_e32 v2, s99
	v_mov_b32_e32 v0, s100
	s_waitcnt lgkmcnt(0)
	v_cmp_eq_u32_e32 vcc, 0, v2
	s_and_saveexec_b64 s[2:3], vcc
	s_cbranch_execz .LBB0_1488
	s_add_u32 s42, s52, 0xffff080
	s_addc_u32 s43, s53, 0
	s_add_u32 s44, s52, 0xffff100
	s_addc_u32 s45, s53, 0
	s_add_u32 s46, s52, 0xffff180
	s_addc_u32 s47, s53, 0
	s_add_u32 s48, s52, 0xffff200
	s_addc_u32 s49, s53, 0
	s_add_u32 s50, s52, 0xffff280
	s_addc_u32 s51, s53, 0
	s_mov_b64 s[18:19], s[52:53]
	s_add_u32 s52, s18, 0xffff300
	s_addc_u32 s53, s19, 0
	s_add_u32 s54, s18, 0xffff380
	s_addc_u32 s55, s19, 0
	s_add_u32 s56, s18, 0xffff400
	v_mov_b32_e32 v3, 0
	v_cmp_eq_u32_e64 s[4:5], 0, v1
	v_cmp_eq_u32_e64 s[6:7], 1, v1
	v_cmp_eq_u32_e64 s[8:9], 2, v1
	v_cmp_eq_u32_e64 s[10:11], 3, v1
	v_cmp_eq_u32_e64 s[12:13], 4, v1
	v_cmp_eq_u32_e64 s[14:15], 5, v1
	v_cmp_eq_u32_e64 s[16:17], 6, v1
	s_addc_u32 s57, s19, 0
	v_cmp_eq_u32_e64 s[18:19], 7, v1
	v_mov_b32_e32 v2, 0
	s_branch .LBB0_1485

.LBB0_1538:
	s_waitcnt vmcnt(0)
	v_mov_b32_e32 v0, v190
	s_barrier
	s_nop 0
	v_cmp_eq_u32_e32 vcc, 0, v0
	s_and_saveexec_b64 s[2:3], vcc
	s_cbranch_execz .LBB0_1563
	v_mov_b32_e32 v1, s101
	v_mov_b32_e32 v2, s99
	v_mov_b32_e32 v0, s100
	s_waitcnt lgkmcnt(0)
	v_cmp_eq_u32_e32 vcc, 0, v2
	s_and_saveexec_b64 s[42:43], vcc
	s_cbranch_execz .LBB0_1545
	s_add_u32 s44, s52, 0xffff080
	s_addc_u32 s45, s53, 0
	s_add_u32 s46, s52, 0xffff100
	s_addc_u32 s47, s53, 0
	s_add_u32 s48, s52, 0xffff180
	s_addc_u32 s49, s53, 0
	s_add_u32 s50, s52, 0xffff200
	s_addc_u32 s51, s53, 0
	s_mov_b64 s[18:19], s[52:53]
	s_add_u32 s52, s18, 0xffff280
	s_addc_u32 s53, s19, 0
	s_add_u32 s54, s18, 0xffff300
	s_addc_u32 s55, s19, 0
	s_add_u32 s56, s18, 0xffff380
	s_addc_u32 s57, s19, 0
	s_add_u32 s58, s18, 0xffff400
	v_mov_b32_e32 v3, 0
	v_cmp_eq_u32_e64 s[4:5], 0, v1
	v_cmp_eq_u32_e64 s[6:7], 1, v1
	v_cmp_eq_u32_e64 s[8:9], 2, v1
	v_cmp_eq_u32_e64 s[10:11], 3, v1
	v_cmp_eq_u32_e64 s[12:13], 4, v1
	v_cmp_eq_u32_e64 s[14:15], 5, v1
	v_cmp_eq_u32_e64 s[16:17], 6, v1
	s_addc_u32 s59, s19, 0
	v_cmp_eq_u32_e64 s[18:19], 7, v1
	v_mov_b32_e32 v2, 0
	s_branch .LBB0_1542

.LBB0_1553:
	s_or_b64 exec, exec, s[6:7]
	v_cvt_f32_u32_e32 v4, v0
	s_waitcnt vmcnt(0)
	v_readfirstlane_b32 s4, v3
	v_rcp_iflag_f32_e32 v4, v4
	s_nop 0
	v_add_u32_e32 v2, s4, v2
	v_add_u32_e32 v6, 1, v2
	v_mul_f32_e32 v3, 0x4f7ffffe, v4
	v_cvt_u32_f32_e32 v3, v3
	v_sub_u32_e32 v4, 0, v0
	v_mul_lo_u32 v4, v4, v3
	v_mul_hi_u32 v4, v3, v4
	v_add_u32_e32 v3, v3, v4
	v_mul_hi_u32 v3, v2, v3
	v_mul_lo_u32 v4, v3, v0
	v_sub_u32_e32 v2, v2, v4
	v_add_u32_e32 v5, 1, v3
	v_cmp_ge_u32_e32 vcc, v2, v0
	v_sub_u32_e32 v4, v2, v0
	s_nop 0
	v_cndmask_b32_e32 v3, v3, v5, vcc
	v_cndmask_b32_e32 v2, v2, v4, vcc
	v_add_u32_e32 v4, 1, v3
	v_cmp_ge_u32_e32 vcc, v2, v0
	s_nop 1
	v_cndmask_b32_e32 v2, v3, v4, vcc
	v_mad_u64_u32 v[4:5], s[4:5], v0, v2, v[0:1]
	s_add_u32 s4, s52, 0xffffe00
	v_cmp_ne_u32_e32 vcc, v6, v4
	s_addc_u32 s5, s53, 0
	s_and_saveexec_b64 s[6:7], vcc
	s_xor_b64 s[6:7], exec, s[6:7]
	s_cbranch_execz .LBB0_1558
	v_mov_b32_e32 v0, 0
	global_load_dword v3, v0, s[4:5] sc1
	s_waitcnt vmcnt(0)
	v_cmp_lt_u32_e32 vcc, v3, v4
	s_and_saveexec_b64 s[8:9], vcc
	s_cbranch_execz .LBB0_1557
	s_mov_b64 s[10:11], 0
.LBB0_1556:
	s_sleep 1
	global_load_dword v3, v0, s[4:5] sc1
	s_waitcnt vmcnt(0)
	v_cmp_ge_u32_e32 vcc, v3, v4
	s_or_b64 s[10:11], vcc, s[10:11]
	s_andn2_b64 exec, exec, s[10:11]
	s_cbranch_execnz .LBB0_1556

.LBB0_1558:
	s_andn2_saveexec_b64 s[6:7], s[6:7]
	s_cbranch_execz .LBB0_1562
	s_mov_b64 s[10:11], exec
	v_mbcnt_lo_u32_b32 v0, s10, 0
	v_mbcnt_hi_u32_b32 v0, s11, v0
	v_cmp_eq_u32_e32 vcc, 0, v0
	s_and_saveexec_b64 s[8:9], vcc
	s_cbranch_execz .LBB0_1561
	s_bcnt1_i32_b64 s10, s[10:11]
	v_mov_b32_e32 v0, 0
	v_mov_b32_e32 v2, s10
	s_nop 0

.LBB0_1636:
	s_waitcnt vmcnt(0)
	s_nop 0
	v_mov_b32_e32 v0, v190
	s_barrier
	s_nop 0
	v_cmp_eq_u32_e32 vcc, 0, v0
	s_and_saveexec_b64 s[0:1], vcc
	s_cbranch_execz .LBB0_1661
	v_mov_b32_e32 v1, s101
	v_mov_b32_e32 v2, s99
	v_mov_b32_e32 v0, s100
	s_waitcnt lgkmcnt(0)
	v_cmp_eq_u32_e32 vcc, 0, v2
	s_and_saveexec_b64 s[2:3], vcc
	s_cbranch_execz .LBB0_1643
	s_add_u32 s42, s52, 0xffff080
	s_addc_u32 s43, s53, 0
	s_add_u32 s44, s52, 0xffff100
	s_addc_u32 s45, s53, 0
	s_add_u32 s46, s52, 0xffff180
	s_addc_u32 s47, s53, 0
	s_add_u32 s48, s52, 0xffff200
	s_addc_u32 s49, s53, 0
	s_add_u32 s50, s52, 0xffff280
	s_addc_u32 s51, s53, 0
	s_mov_b64 s[18:19], s[52:53]
	s_add_u32 s52, s18, 0xffff300
	s_addc_u32 s53, s19, 0
	s_add_u32 s54, s18, 0xffff380
	s_addc_u32 s55, s19, 0
	s_add_u32 s56, s18, 0xffff400
	s_mov_b64 s[58:59], s[16:17]
	v_mov_b32_e32 v3, 0
	v_cmp_eq_u32_e64 s[4:5], 0, v1
	v_cmp_eq_u32_e64 s[6:7], 1, v1
	v_cmp_eq_u32_e64 s[8:9], 2, v1
	v_cmp_eq_u32_e64 s[10:11], 3, v1
	v_cmp_eq_u32_e64 s[12:13], 4, v1
	v_cmp_eq_u32_e64 s[14:15], 5, v1
	v_cmp_eq_u32_e64 s[16:17], 6, v1
	s_addc_u32 s57, s19, 0
	v_cmp_eq_u32_e64 s[18:19], 7, v1
	v_mov_b32_e32 v2, 0
	s_branch .LBB0_1640

.LBB0_1845:
	s_waitcnt vmcnt(0)
	v_mov_b32_e32 v0, v190
	s_barrier
	s_nop 0
	v_cmp_eq_u32_e32 vcc, 0, v0
	s_and_saveexec_b64 s[0:1], vcc
	s_cbranch_execz .LBB0_1870
	v_mov_b32_e32 v1, s101
	v_mov_b32_e32 v2, s99
	v_mov_b32_e32 v0, s100
	s_waitcnt lgkmcnt(0)
	v_cmp_eq_u32_e32 vcc, 0, v2
	s_and_saveexec_b64 s[2:3], vcc
	s_cbranch_execz .LBB0_1852
	s_add_u32 s40, s52, 0xffff080
	s_addc_u32 s41, s53, 0
	s_add_u32 s42, s52, 0xffff100
	s_addc_u32 s43, s53, 0
	s_add_u32 s44, s52, 0xffff180
	s_addc_u32 s45, s53, 0
	s_add_u32 s46, s52, 0xffff200
	s_addc_u32 s47, s53, 0
	s_add_u32 s48, s52, 0xffff280
	s_addc_u32 s49, s53, 0
	s_add_u32 s50, s52, 0xffff300
	s_addc_u32 s51, s53, 0
	s_mov_b64 s[18:19], s[52:53]
	s_add_u32 s52, s18, 0xffff380
	s_addc_u32 s53, s19, 0
	s_add_u32 s54, s18, 0xffff400
	v_mov_b32_e32 v3, 0
	v_cmp_eq_u32_e64 s[4:5], 0, v1
	v_cmp_eq_u32_e64 s[6:7], 1, v1
	v_cmp_eq_u32_e64 s[8:9], 2, v1
	v_cmp_eq_u32_e64 s[10:11], 3, v1
	v_cmp_eq_u32_e64 s[12:13], 4, v1
	v_cmp_eq_u32_e64 s[14:15], 5, v1
	v_cmp_eq_u32_e64 s[16:17], 6, v1
	s_addc_u32 s55, s19, 0
	v_cmp_eq_u32_e64 s[18:19], 7, v1
	v_mov_b32_e32 v2, 0
	s_branch .LBB0_1849

.LBB0_2162:
	s_waitcnt vmcnt(0)
	v_mov_b32_e32 v0, v190
	s_waitcnt vmcnt(0)
	s_barrier
	s_nop 0
	v_cmp_eq_u32_e32 vcc, 0, v0
	s_and_saveexec_b64 s[0:1], vcc
	s_cbranch_execz .LBB0_2187
	v_mov_b32_e32 v1, s101
	v_mov_b32_e32 v2, s99
	v_mov_b32_e32 v0, s100
	s_waitcnt lgkmcnt(0)
	v_cmp_eq_u32_e32 vcc, 0, v2
	s_and_saveexec_b64 s[2:3], vcc
	s_cbranch_execz .LBB0_2169
	s_add_u32 s40, s52, 0xffff080
	s_addc_u32 s41, s53, 0
	s_add_u32 s42, s52, 0xffff100
	s_addc_u32 s43, s53, 0
	s_add_u32 s44, s52, 0xffff180
	s_addc_u32 s45, s53, 0
	s_add_u32 s46, s52, 0xffff200
	s_addc_u32 s47, s53, 0
	s_add_u32 s48, s52, 0xffff280
	s_addc_u32 s49, s53, 0
	s_add_u32 s50, s52, 0xffff300
	s_addc_u32 s51, s53, 0
	s_mov_b64 s[18:19], s[52:53]
	s_add_u32 s52, s18, 0xffff380
	s_addc_u32 s53, s19, 0
	s_add_u32 s54, s18, 0xffff400
	v_mov_b32_e32 v3, 0
	v_cmp_eq_u32_e64 s[4:5], 0, v1
	v_cmp_eq_u32_e64 s[6:7], 1, v1
	v_cmp_eq_u32_e64 s[8:9], 2, v1
	v_cmp_eq_u32_e64 s[10:11], 3, v1
	v_cmp_eq_u32_e64 s[12:13], 4, v1
	v_cmp_eq_u32_e64 s[14:15], 5, v1
	v_cmp_eq_u32_e64 s[16:17], 6, v1
	s_addc_u32 s55, s19, 0
	v_cmp_eq_u32_e64 s[18:19], 7, v1
	v_mov_b32_e32 v2, 0
	s_branch .LBB0_2166

.LBB0_2495:
	s_waitcnt vmcnt(0)
	v_mov_b32_e32 v0, v190
	s_barrier
	s_nop 0
	v_cmp_eq_u32_e32 vcc, 0, v0
	s_and_saveexec_b64 s[0:1], vcc
	v_readlane_b32 s56, v255, 43
	s_mul_i32 s28, s86, 0x300
	v_readlane_b32 s57, v255, 44
	s_cbranch_execz .LBB0_2520
	v_mov_b32_e32 v1, s101
	v_mov_b32_e32 v2, s99
	v_mov_b32_e32 v0, s100
	s_waitcnt lgkmcnt(0)
	v_cmp_eq_u32_e32 vcc, 0, v2
	s_and_saveexec_b64 s[2:3], vcc
	s_cbranch_execz .LBB0_2502
	s_add_u32 s40, s52, 0xffff080
	s_addc_u32 s41, s53, 0
	s_add_u32 s42, s52, 0xffff100
	s_addc_u32 s43, s53, 0
	s_add_u32 s44, s52, 0xffff180
	s_addc_u32 s45, s53, 0
	s_add_u32 s46, s52, 0xffff200
	s_addc_u32 s47, s53, 0
	s_add_u32 s48, s52, 0xffff280
	s_addc_u32 s49, s53, 0
	s_add_u32 s50, s52, 0xffff300
	s_addc_u32 s51, s53, 0
	s_mov_b64 s[18:19], s[52:53]
	s_add_u32 s52, s18, 0xffff380
	s_addc_u32 s53, s19, 0
	s_add_u32 s54, s18, 0xffff400
	v_mov_b32_e32 v3, 0
	v_cmp_eq_u32_e64 s[4:5], 0, v1
	v_cmp_eq_u32_e64 s[6:7], 1, v1
	v_cmp_eq_u32_e64 s[8:9], 2, v1
	v_cmp_eq_u32_e64 s[10:11], 3, v1
	v_cmp_eq_u32_e64 s[12:13], 4, v1
	v_cmp_eq_u32_e64 s[14:15], 5, v1
	v_cmp_eq_u32_e64 s[16:17], 6, v1
	s_addc_u32 s55, s19, 0
	v_cmp_eq_u32_e64 s[18:19], 7, v1
	v_mov_b32_e32 v2, 0
	s_branch .LBB0_2499

.LBB0_2570:
	s_waitcnt vmcnt(0)
	v_mov_b32_e32 v0, v190
	s_barrier
	s_nop 0
	v_cmp_eq_u32_e32 vcc, 0, v0
	s_and_saveexec_b64 s[36:37], vcc
	s_cbranch_execz .LBB0_2595
	v_mov_b32_e32 v1, s101
	v_mov_b32_e32 v2, s99
	v_mov_b32_e32 v0, s100
	s_waitcnt lgkmcnt(0)
	v_cmp_eq_u32_e32 vcc, 0, v2
	s_and_saveexec_b64 s[38:39], vcc
	s_cbranch_execz .LBB0_2577
	s_add_u32 s40, s52, 0xffff080
	s_addc_u32 s41, s53, 0
	s_add_u32 s42, s52, 0xffff100
	s_addc_u32 s43, s53, 0
	s_add_u32 s44, s52, 0xffff180
	s_addc_u32 s45, s53, 0
	s_add_u32 s46, s52, 0xffff200
	s_addc_u32 s47, s53, 0
	s_add_u32 s48, s52, 0xffff280
	s_addc_u32 s49, s53, 0
	s_add_u32 s50, s52, 0xffff300
	s_addc_u32 s51, s53, 0
	s_mov_b64 s[14:15], s[52:53]
	s_add_u32 s52, s14, 0xffff380
	s_addc_u32 s53, s15, 0
	s_add_u32 s54, s14, 0xffff400
	v_mov_b32_e32 v3, 0
	v_cmp_eq_u32_e64 s[0:1], 0, v1
	v_cmp_eq_u32_e64 s[2:3], 1, v1
	v_cmp_eq_u32_e64 s[4:5], 2, v1
	v_cmp_eq_u32_e64 s[6:7], 3, v1
	v_cmp_eq_u32_e64 s[8:9], 4, v1
	v_cmp_eq_u32_e64 s[10:11], 5, v1
	v_cmp_eq_u32_e64 s[12:13], 6, v1
	s_addc_u32 s55, s15, 0
	v_cmp_eq_u32_e64 s[14:15], 7, v1
	v_mov_b32_e32 v2, 0
	s_branch .LBB0_2574

.LBB0_2585:
	s_or_b64 exec, exec, s[2:3]
	v_cvt_f32_u32_e32 v4, v0
	s_waitcnt vmcnt(0)
	v_readfirstlane_b32 s0, v3
	v_rcp_iflag_f32_e32 v4, v4
	s_nop 0
	v_add_u32_e32 v2, s0, v2
	v_add_u32_e32 v6, 1, v2
	v_mul_f32_e32 v3, 0x4f7ffffe, v4
	v_cvt_u32_f32_e32 v3, v3
	v_sub_u32_e32 v4, 0, v0
	v_mul_lo_u32 v4, v4, v3
	v_mul_hi_u32 v4, v3, v4
	v_add_u32_e32 v3, v3, v4
	v_mul_hi_u32 v3, v2, v3
	v_mul_lo_u32 v4, v3, v0
	v_sub_u32_e32 v2, v2, v4
	v_add_u32_e32 v5, 1, v3
	v_cmp_ge_u32_e32 vcc, v2, v0
	v_sub_u32_e32 v4, v2, v0
	s_nop 0
	v_cndmask_b32_e32 v3, v3, v5, vcc
	v_cndmask_b32_e32 v2, v2, v4, vcc
	v_add_u32_e32 v4, 1, v3
	v_cmp_ge_u32_e32 vcc, v2, v0
	s_nop 1
	v_cndmask_b32_e32 v2, v3, v4, vcc
	v_mad_u64_u32 v[4:5], s[0:1], v0, v2, v[0:1]
	s_add_u32 s0, s52, 0xffffe00
	v_cmp_ne_u32_e32 vcc, v6, v4
	s_addc_u32 s1, s53, 0
	s_and_saveexec_b64 s[2:3], vcc
	s_xor_b64 s[2:3], exec, s[2:3]
	s_cbranch_execz .LBB0_2590
	v_mov_b32_e32 v0, 0
	global_load_dword v3, v0, s[0:1] sc1
	s_waitcnt vmcnt(0)
	v_cmp_lt_u32_e32 vcc, v3, v4
	s_and_saveexec_b64 s[4:5], vcc
	s_cbranch_execz .LBB0_2589
	s_mov_b64 s[6:7], 0

	.amdhsa_kernel _Z4mega6Params
		.amdhsa_group_segment_fixed_size 81920
		.amdhsa_private_segment_fixed_size 0
		.amdhsa_kernarg_size 520
		.amdhsa_user_sgpr_count 2
		.amdhsa_user_sgpr_dispatch_ptr 0
		.amdhsa_user_sgpr_queue_ptr 0
		.amdhsa_user_sgpr_kernarg_segment_ptr 1
		.amdhsa_user_sgpr_dispatch_id 0
		.amdhsa_user_sgpr_kernarg_preload_length 0
		.amdhsa_user_sgpr_kernarg_preload_offset 0
		.amdhsa_user_sgpr_private_segment_size 0
		.amdhsa_uses_dynamic_stack 0
		.amdhsa_enable_private_segment 0
		.amdhsa_system_sgpr_workgroup_id_x 1
		.amdhsa_system_sgpr_workgroup_id_y 0
		.amdhsa_system_sgpr_workgroup_id_z 0
		.amdhsa_system_sgpr_workgroup_info 0
		.amdhsa_system_vgpr_workitem_id 2
		.amdhsa_next_free_vgpr 256
		.amdhsa_next_free_sgpr 102
		.amdhsa_accum_offset 256
		.amdhsa_reserve_vcc 1
		.amdhsa_float_round_mode_32 0
		.amdhsa_float_round_mode_16_64 0
		.amdhsa_float_denorm_mode_32 3
		.amdhsa_float_denorm_mode_16_64 3
		.amdhsa_dx10_clamp 1
		.amdhsa_ieee_mode 1
		.amdhsa_fp16_overflow 0
		.amdhsa_tg_split 0
		.amdhsa_exception_fp_ieee_invalid_op 0
		.amdhsa_exception_fp_denorm_src 0
		.amdhsa_exception_fp_ieee_div_zero 0
		.amdhsa_exception_fp_ieee_overflow 0
		.amdhsa_exception_fp_ieee_underflow 0
		.amdhsa_exception_fp_ieee_inexact 0
		.amdhsa_exception_int_div_zero 0
	.end_amdhsa_kernel

amdhsa.kernels:
  - .agpr_count:     0
    .args:
      - .offset:         0
        .size:           264
        .value_kind:     by_value
      - .offset:         264
        .size:           4
        .value_kind:     hidden_block_count_x
      - .offset:         268
        .size:           4
        .value_kind:     hidden_block_count_y
      - .offset:         272
        .size:           4
        .value_kind:     hidden_block_count_z
      - .offset:         276
        .size:           2
        .value_kind:     hidden_group_size_x
      - .offset:         278
        .size:           2
        .value_kind:     hidden_group_size_y
      - .offset:         280
        .size:           2
        .value_kind:     hidden_group_size_z
      - .offset:         282
        .size:           2
        .value_kind:     hidden_remainder_x
      - .offset:         284
        .size:           2
        .value_kind:     hidden_remainder_y
      - .offset:         286
        .size:           2
        .value_kind:     hidden_remainder_z
      - .offset:         304
        .size:           8
        .value_kind:     hidden_global_offset_x
      - .offset:         312
        .size:           8
        .value_kind:     hidden_global_offset_y
      - .offset:         320
        .size:           8
        .value_kind:     hidden_global_offset_z
      - .offset:         328
        .size:           2
        .value_kind:     hidden_grid_dims
      - .offset:         352
        .size:           8
        .value_kind:     hidden_multigrid_sync_arg
    .group_segment_fixed_size: 81920
    .kernarg_segment_align: 8
    .kernarg_segment_size: 520
    .language:       OpenCL C
    .language_version:
      - 2
      - 0
    .max_flat_workgroup_size: 256
    .name:           _Z4mega6Params
    .private_segment_fixed_size: 0
    .sgpr_count:     108
    .sgpr_spill_count: 118
    .symbol:         _Z4mega6Params.kd
    .uniform_work_group_size: 1
    .uses_dynamic_stack: false
    .vgpr_count:     256
    .vgpr_spill_count: 0
    .wavefront_size: 64
